# v28 + the same output-stage load batching for the context-query attention instance
# speedup vs baseline: 1.0042x; 1.0010x over previous
; #define LAS __attribute__((address_space(3)))
; DI void attn_unit(LAS unsigned char* lds, int tid, const bf16* __restrict__ P, const bf16* __restrict__ Vt, bf16* MG, int b, int h, int qrow0, int jt0, int jt1,
;                   float lam, float oscale, const float* subg) {
;     ...
;     __syncthreads();
;     const float l = lrun + __shfl_xor(lrun, 32);
;     const float inv = (m ? lam : 1.0f) / l;
;     LAS float* X = (LAS float*)lds + qb * 4096 + lane;
;     if (m) {
; #pragma unroll
;         for (int es = 0; es < 4; ++es)
; #pragma unroll
;             for (int i = 0; i < 16; ++i) X[(es * 16 + i) * 64] = O[es][i] * inv;
;     }
;     __syncthreads();
;     if (!m) {
;         float ss = 0.f;
; #pragma unroll
;         for (int es = 0; es < 4; ++es)
; #pragma unroll
;             for (int i = 0; i < 16; ++i) { const float o = O[es][i] * inv - X[(es * 16 + i) * 64]; O[es][i] = o; ss += o * o; }
.LBB0_783:
	s_or_b64 exec, exec, s[2:3]
	s_waitcnt lgkmcnt(0)
	s_barrier
	s_and_saveexec_b64 s[2:3], s[0:1]
	s_cbranch_execz .LBB0_761
	ds_read2st64_b32 v[88:89], v82 offset1:1
	ds_read2st64_b32 v[90:91], v82 offset0:2 offset1:3
	ds_read2st64_b32 v[104:105], v82 offset0:4 offset1:5
	ds_read2st64_b32 v[96:97], v82 offset0:6 offset1:7
	ds_read2st64_b32 v[106:107], v82 offset0:8 offset1:9
	s_waitcnt vmcnt(2)
	ds_read2st64_b32 v[132:133], v82 offset0:10 offset1:11
	ds_read2st64_b32 v[128:129], v82 offset0:12 offset1:13
	ds_read2st64_b32 v[134:135], v82 offset0:14 offset1:15
	ds_read2st64_b32 v[124:125], v82 offset0:16 offset1:17
	ds_read2st64_b32 v[130:131], v82 offset0:18 offset1:19
	ds_read2st64_b32 v[120:121], v82 offset0:20 offset1:21
	ds_read2st64_b32 v[126:127], v82 offset0:22 offset1:23
	ds_read2st64_b32 v[116:117], v82 offset0:24 offset1:25
	ds_read2st64_b32 v[122:123], v82 offset0:26 offset1:27
	ds_read2st64_b32 v[112:113], v82 offset0:28 offset1:29
	ds_read2st64_b32 v[118:119], v82 offset0:30 offset1:31
	ds_read2st64_b32 v[102:103], v82 offset0:32 offset1:33
	ds_read2st64_b32 v[114:115], v82 offset0:34 offset1:35
	ds_read2st64_b32 v[98:99], v82 offset0:36 offset1:37
	ds_read2st64_b32 v[108:109], v82 offset0:38 offset1:39
	ds_read2st64_b32 v[92:93], v82 offset0:40 offset1:41
	ds_read2st64_b32 v[100:101], v82 offset0:42 offset1:43
	ds_read2st64_b32 v[86:87], v82 offset0:44 offset1:45
	ds_read2st64_b32 v[94:95], v82 offset0:46 offset1:47
	ds_read2st64_b32 v[80:81], v82 offset0:48 offset1:49
	ds_read2st64_b32 v[84:85], v82 offset0:50 offset1:51
	ds_read2st64_b32 v[76:77], v82 offset0:52 offset1:53
	ds_read2st64_b32 v[78:79], v82 offset0:54 offset1:55
	ds_read2st64_b32 v[72:73], v82 offset0:56 offset1:57
	ds_read2st64_b32 v[64:65], v82 offset0:58 offset1:59
	s_waitcnt lgkmcnt(14)
	v_pk_fma_f32 v[96:97], v[54:55], v[68:69], v[96:97] op_sel_hi:[1,0,1] neg_lo:[0,0,1] neg_hi:[0,0,1]
	v_pk_fma_f32 v[104:105], v[52:53], v[68:69], v[104:105] op_sel_hi:[1,0,1] neg_lo:[0,0,1] neg_hi:[0,0,1]
	v_pk_fma_f32 v[106:107], v[56:57], v[68:69], v[106:107] op_sel_hi:[1,0,1] neg_lo:[0,0,1] neg_hi:[0,0,1]
	v_pk_fma_f32 v[62:63], v[62:63], v[68:69], v[134:135] op_sel_hi:[1,0,1] neg_lo:[0,0,1] neg_hi:[0,0,1]
	s_waitcnt lgkmcnt(0)
	v_pk_fma_f32 v[64:65], v[10:11], v[68:69], v[64:65] op_sel_hi:[1,0,1] neg_lo:[0,0,1] neg_hi:[0,0,1]
	ds_read2st64_b32 v[10:11], v82 offset0:60 offset1:61
	v_pk_fma_f32 v[60:61], v[60:61], v[68:69], v[128:129] op_sel_hi:[1,0,1] neg_lo:[0,0,1] neg_hi:[0,0,1]
	v_pk_fma_f32 v[56:57], v[34:35], v[68:69], v[130:131] op_sel_hi:[1,0,1] neg_lo:[0,0,1] neg_hi:[0,0,1]
	v_pk_fma_f32 v[54:55], v[36:37], v[68:69], v[120:121] op_sel_hi:[1,0,1] neg_lo:[0,0,1] neg_hi:[0,0,1]
	v_pk_fma_f32 v[42:43], v[42:43], v[68:69], v[122:123] op_sel_hi:[1,0,1] neg_lo:[0,0,1] neg_hi:[0,0,1]
	s_waitcnt lgkmcnt(0)
	v_pk_fma_f32 v[66:67], v[12:13], v[68:69], v[10:11] op_sel_hi:[1,0,1] neg_lo:[0,0,1] neg_hi:[0,0,1]
	ds_read2st64_b32 v[10:11], v82 offset0:62 offset1:63
	v_pk_fma_f32 v[82:83], v[50:51], v[68:69], v[90:91] op_sel_hi:[1,0,1] neg_lo:[0,0,1] neg_hi:[0,0,1]
	v_pk_fma_f32 v[90:91], v[48:49], v[68:69], v[88:89] op_sel_hi:[1,0,1] neg_lo:[0,0,1] neg_hi:[0,0,1]
	s_waitcnt vmcnt(1)
	v_pk_mul_f32 v[138:139], v[82:83], v[82:83]
	s_waitcnt vmcnt(0)
	v_pk_mul_f32 v[140:141], v[90:91], v[90:91]
	s_waitcnt lgkmcnt(0)
	v_pk_fma_f32 v[14:15], v[14:15], v[68:69], v[10:11] op_sel_hi:[1,0,1] neg_lo:[0,0,1] neg_hi:[0,0,1]
	v_pk_fma_f32 v[88:89], v[58:59], v[68:69], v[132:133] op_sel_hi:[1,0,1] neg_lo:[0,0,1] neg_hi:[0,0,1]
	v_pk_fma_f32 v[58:59], v[32:33], v[68:69], v[124:125] op_sel_hi:[1,0,1] neg_lo:[0,0,1] neg_hi:[0,0,1]
	v_pk_fma_f32 v[50:51], v[38:39], v[68:69], v[126:127] op_sel_hi:[1,0,1] neg_lo:[0,0,1] neg_hi:[0,0,1]
	v_pk_fma_f32 v[52:53], v[40:41], v[68:69], v[116:117] op_sel_hi:[1,0,1] neg_lo:[0,0,1] neg_hi:[0,0,1]
	v_pk_fma_f32 v[40:41], v[46:47], v[68:69], v[118:119] op_sel_hi:[1,0,1] neg_lo:[0,0,1] neg_hi:[0,0,1]
	v_pk_fma_f32 v[44:45], v[44:45], v[68:69], v[112:113] op_sel_hi:[1,0,1] neg_lo:[0,0,1] neg_hi:[0,0,1]
	v_pk_fma_f32 v[36:37], v[18:19], v[68:69], v[114:115] op_sel_hi:[1,0,1] neg_lo:[0,0,1] neg_hi:[0,0,1]
	v_pk_fma_f32 v[38:39], v[16:17], v[68:69], v[102:103] op_sel_hi:[1,0,1] neg_lo:[0,0,1] neg_hi:[0,0,1]
	v_pk_fma_f32 v[32:33], v[22:23], v[68:69], v[108:109] op_sel_hi:[1,0,1] neg_lo:[0,0,1] neg_hi:[0,0,1]
	v_pk_fma_f32 v[34:35], v[20:21], v[68:69], v[98:99] op_sel_hi:[1,0,1] neg_lo:[0,0,1] neg_hi:[0,0,1]
	v_pk_fma_f32 v[22:23], v[26:27], v[68:69], v[100:101] op_sel_hi:[1,0,1] neg_lo:[0,0,1] neg_hi:[0,0,1]
	v_pk_fma_f32 v[26:27], v[24:25], v[68:69], v[92:93] op_sel_hi:[1,0,1] neg_lo:[0,0,1] neg_hi:[0,0,1]
	v_pk_fma_f32 v[20:21], v[30:31], v[68:69], v[94:95] op_sel_hi:[1,0,1] neg_lo:[0,0,1] neg_hi:[0,0,1]
	v_pk_fma_f32 v[24:25], v[28:29], v[68:69], v[86:87] op_sel_hi:[1,0,1] neg_lo:[0,0,1] neg_hi:[0,0,1]
	v_pk_fma_f32 v[16:17], v[2:3], v[68:69], v[84:85] op_sel_hi:[1,0,1] neg_lo:[0,0,1] neg_hi:[0,0,1]
	v_pk_fma_f32 v[18:19], v[0:1], v[68:69], v[80:81] op_sel_hi:[1,0,1] neg_lo:[0,0,1] neg_hi:[0,0,1]
	v_pk_fma_f32 v[2:3], v[6:7], v[68:69], v[78:79] op_sel_hi:[1,0,1] neg_lo:[0,0,1] neg_hi:[0,0,1]
	v_pk_fma_f32 v[4:5], v[4:5], v[68:69], v[76:77] op_sel_hi:[1,0,1] neg_lo:[0,0,1] neg_hi:[0,0,1]
	v_pk_fma_f32 v[0:1], v[8:9], v[68:69], v[72:73] op_sel_hi:[1,0,1] neg_lo:[0,0,1] neg_hi:[0,0,1]
	v_add_f32_e32 v68, v140, v141
	v_lshlrev_b64 v[10:11], 11, v[156:157]
	v_readlane_b32 s12, v253, 6
	v_add_f32_e32 v68, v68, v138
	v_lshl_add_u64 v[10:11], s[70:71], 0, v[10:11]
	v_readlane_b32 s13, v253, 7
	v_pk_mul_f32 v[142:143], v[104:105], v[104:105]
; DI void attn_unit(LAS unsigned char* lds, int tid, const bf16* __restrict__ P, const bf16* __restrict__ Vt, bf16* MG, int b, int h, int qrow0, int jt0, int jt1,
;                   float lam, float oscale, const float* subg) {
;     ...
;         float ss = 0.f;
; #pragma unroll
;         for (int es = 0; es < 4; ++es)
; #pragma unroll
;             for (int i = 0; i < 16; ++i) { const float o = O[es][i] * inv - X[(es * 16 + i) * 64]; O[es][i] = o; ss += o * o; }
;         ss += __shfl_xor(ss, 32);
;         const float rn = (1.0f / sqrtf(ss * (1.0f / 128.0f) + 1e-6f)) * oscale;
; #pragma unroll
;         for (int es = 0; es < 4; ++es)
; #pragma unroll
;             for (int g4 = 0; g4 < 4; ++g4) {
;                 const int e = es * 32 + 8 * g4 + 4 * hi;
;                 const f32x4 gv = *(const f32x4*)(subg + e);
	v_add_f32_e32 v68, v68, v139
	v_lshl_add_u64 v[136:137], v[10:11], 0, s[12:13]
	v_lshlrev_b32_e32 v146, 3, v167
	v_add_f32_e32 v68, v68, v142
	v_lshl_add_u64 v[48:49], v[136:137], 0, v[146:147]
	v_pk_mul_f32 v[136:137], v[96:97], v[96:97]
	v_add_f32_e32 v68, v68, v143
	v_add_f32_e32 v68, v68, v136
	v_pk_mul_f32 v[150:151], v[106:107], v[106:107]
	v_add_f32_e32 v68, v68, v137
	v_add_f32_e32 v68, v68, v150
	v_pk_mul_f32 v[132:133], v[88:89], v[88:89]
	v_add_f32_e32 v68, v68, v151
	v_add_f32_e32 v68, v68, v132
	v_pk_mul_f32 v[128:129], v[60:61], v[60:61]
	v_add_f32_e32 v68, v68, v133
	v_add_f32_e32 v68, v68, v128
	v_pk_mul_f32 v[134:135], v[62:63], v[62:63]
	v_add_f32_e32 v68, v68, v129
	v_add_f32_e32 v68, v68, v134
	v_pk_mul_f32 v[124:125], v[58:59], v[58:59]
	v_add_f32_e32 v68, v68, v135
	v_add_f32_e32 v68, v68, v124
	v_pk_mul_f32 v[130:131], v[56:57], v[56:57]
	v_add_f32_e32 v68, v68, v125
	v_add_f32_e32 v68, v68, v130
	v_readlane_b32 s4, v253, 47
	v_pk_mul_f32 v[120:121], v[54:55], v[54:55]
	v_add_f32_e32 v68, v68, v131
	v_readlane_b32 s5, v253, 48
	v_add_f32_e32 v68, v68, v120
	v_pk_mul_f32 v[126:127], v[50:51], v[50:51]
	v_add_f32_e32 v68, v68, v121
	v_add_f32_e32 v68, v68, v126
	v_pk_mul_f32 v[116:117], v[52:53], v[52:53]
	global_load_dwordx4 v[10:13], v154, s[4:5]
	global_load_dwordx4 v[168:171], v154, s[4:5] offset:32
	global_load_dwordx4 v[172:175], v154, s[4:5] offset:64
	global_load_dwordx4 v[176:179], v154, s[4:5] offset:96
	global_load_dwordx4 v[180:183], v154, s[4:5] offset:128
	global_load_dwordx4 v[184:187], v154, s[4:5] offset:160
	global_load_dwordx4 v[188:191], v154, s[4:5] offset:192
	global_load_dwordx4 v[192:195], v154, s[4:5] offset:224
	global_load_dwordx4 v[196:199], v154, s[4:5] offset:256
	global_load_dwordx4 v[200:203], v154, s[4:5] offset:288
	global_load_dwordx4 v[204:207], v154, s[4:5] offset:320
	global_load_dwordx4 v[218:221], v154, s[4:5] offset:352
	global_load_dwordx4 v[222:225], v154, s[4:5] offset:384
	global_load_dwordx4 v[226:229], v154, s[4:5] offset:416
	global_load_dwordx4 v[230:233], v154, s[4:5] offset:448
	global_load_dwordx4 v[234:237], v154, s[4:5] offset:480
	v_add_f32_e32 v68, v68, v127
	v_add_f32_e32 v68, v68, v116
	v_pk_mul_f32 v[122:123], v[42:43], v[42:43]
	v_add_f32_e32 v68, v68, v117
	v_add_f32_e32 v68, v68, v122
	v_pk_mul_f32 v[112:113], v[44:45], v[44:45]
	v_add_f32_e32 v68, v68, v123
	v_add_f32_e32 v68, v68, v112
	v_pk_mul_f32 v[46:47], v[40:41], v[40:41]
	v_add_f32_e32 v68, v68, v113
	v_add_f32_e32 v46, v68, v46
	v_pk_mul_f32 v[102:103], v[38:39], v[38:39]
	v_add_f32_e32 v46, v46, v47
	v_add_f32_e32 v46, v46, v102
	v_pk_mul_f32 v[114:115], v[36:37], v[36:37]
	v_add_f32_e32 v46, v46, v103
	v_add_f32_e32 v46, v46, v114
	v_pk_mul_f32 v[98:99], v[34:35], v[34:35]
	v_add_f32_e32 v46, v46, v115
	v_add_f32_e32 v46, v46, v98
	v_pk_mul_f32 v[108:109], v[32:33], v[32:33]
	v_add_f32_e32 v46, v46, v99
	v_add_f32_e32 v46, v46, v108
	v_pk_mul_f32 v[92:93], v[26:27], v[26:27]
	v_add_f32_e32 v46, v46, v109
	v_add_f32_e32 v46, v46, v92
	v_pk_mul_f32 v[100:101], v[22:23], v[22:23]
	v_add_f32_e32 v46, v46, v93
	v_add_f32_e32 v46, v46, v100
	v_pk_mul_f32 v[28:29], v[24:25], v[24:25]
	v_add_f32_e32 v46, v46, v101
	v_add_f32_e32 v28, v46, v28
	v_pk_mul_f32 v[30:31], v[20:21], v[20:21]
	v_add_f32_e32 v28, v28, v29
	v_add_f32_e32 v28, v28, v30
	v_pk_mul_f32 v[80:81], v[18:19], v[18:19]
	v_add_f32_e32 v28, v28, v31
	v_add_f32_e32 v28, v28, v80
	v_pk_mul_f32 v[84:85], v[16:17], v[16:17]
	v_add_f32_e32 v28, v28, v81
	v_add_f32_e32 v28, v28, v84
	v_pk_mul_f32 v[76:77], v[4:5], v[4:5]
	v_add_f32_e32 v28, v28, v85
	v_add_f32_e32 v28, v28, v76
	v_pk_mul_f32 v[6:7], v[2:3], v[2:3]
	v_add_f32_e32 v28, v28, v77
	v_add_f32_e32 v6, v28, v6
	v_pk_mul_f32 v[8:9], v[0:1], v[0:1]
	v_add_f32_e32 v6, v6, v7
	v_add_f32_e32 v6, v6, v8
	v_pk_mul_f32 v[70:71], v[64:65], v[64:65]
	v_add_f32_e32 v6, v6, v9
	v_add_f32_e32 v6, v6, v70
	v_pk_mul_f32 v[74:75], v[66:67], v[66:67]
	v_add_f32_e32 v6, v6, v71
	v_add_f32_e32 v6, v6, v74
	v_pk_mul_f32 v[110:111], v[14:15], v[14:15]
	v_add_f32_e32 v6, v6, v75
	v_add_f32_e32 v6, v6, v110
	v_add_f32_e32 v6, v6, v111
	ds_bpermute_b32 v7, v69, v6
	v_readlane_b32 s14, v253, 8
	v_readlane_b32 s15, v253, 9
	v_readlane_b32 s16, v253, 10
	v_readlane_b32 s17, v253, 11
	s_waitcnt lgkmcnt(0)
	v_add_f32_e32 v6, v6, v7
	v_mov_b32_e32 v7, 0x358637bd
	v_fmamk_f32 v6, v6, 0x3c000000, v7
	v_cmp_gt_f32_e32 vcc, s65, v6
	v_mul_f32_e32 v7, 0x4f800000, v6
	v_readlane_b32 s18, v253, 12
	v_cndmask_b32_e32 v6, v6, v7, vcc
	v_sqrt_f32_e32 v7, v6
	v_readlane_b32 s19, v253, 13
	v_readlane_b32 s20, v253, 14
	v_readlane_b32 s21, v253, 15
	v_add_u32_e32 v8, -1, v7
	v_fma_f32 v9, -v8, v7, v6
	v_cmp_ge_f32_e64 s[0:1], 0, v9
	v_add_u32_e32 v9, 1, v7
	v_readlane_b32 s22, v253, 16
	v_cndmask_b32_e64 v8, v7, v8, s[0:1]
	v_fma_f32 v7, -v9, v7, v6
	v_cmp_lt_f32_e64 s[0:1], 0, v7
	v_readlane_b32 s23, v253, 17
	v_readlane_b32 s24, v253, 18
	v_cndmask_b32_e64 v7, v8, v9, s[0:1]
	v_mul_f32_e32 v8, 0x37800000, v7
	v_cndmask_b32_e32 v7, v7, v8, vcc
	v_cmp_class_f32_e32 vcc, v6, v208
	v_readlane_b32 s25, v253, 19
	v_readlane_b32 s26, v253, 20
	v_cndmask_b32_e32 v6, v7, v6, vcc
	v_div_scale_f32 v7, s[0:1], v6, v6, 1.0
	v_rcp_f32_e32 v8, v7
	v_readlane_b32 s27, v253, 21
	v_fma_f32 v9, -v7, v8, 1.0
	v_fmac_f32_e32 v8, v9, v8
	v_div_scale_f32 v9, vcc, 1.0, v6, 1.0
	v_mul_f32_e32 v28, v9, v8
	v_fma_f32 v29, -v7, v28, v9
	v_fmac_f32_e32 v28, v29, v8
	v_fma_f32 v7, -v7, v28, v9
	v_div_fmas_f32 v7, v7, v8, v28
	v_div_fixup_f32 v6, v7, v6, 1.0
	v_mul_f32_e32 v6, v166, v6
	v_pk_mul_f32 v[8:9], v[90:91], v[6:7] op_sel_hi:[1,0]
	v_pk_mul_f32 v[4:5], v[4:5], v[6:7] op_sel_hi:[1,0]
	s_waitcnt vmcnt(0)
; DI unsigned pk2(float lo, float hi) { f32x2 v = {lo, hi}; bf16x2_t b = __builtin_convertvector(v, bf16x2_t); return __builtin_bit_cast(unsigned, b); }
; DI void attn_unit(LAS unsigned char* lds, int tid, const bf16* __restrict__ P, const bf16* __restrict__ Vt, bf16* MG, int b, int h, int qrow0, int jt0, int jt1,
;                   float lam, float oscale, const float* subg) {
;     ...
; #pragma unroll
;         for (int es = 0; es < 4; ++es)
; #pragma unroll
;             for (int g4 = 0; g4 < 4; ++g4) {
;                 const int e = es * 32 + 8 * g4 + 4 * hi;
;                 const f32x4 gv = *(const f32x4*)(subg + e);
;                 u32x2 w; w.x = pk2(O[es][4 * g4 + 0] * rn * gv.x, O[es][4 * g4 + 1] * rn * gv.y); w.y = pk2(O[es][4 * g4 + 2] * rn * gv.z, O[es][4 * g4 + 3] * rn * gv.w);
;                 *(u32x2*)(MG + (size_t)qrow * DM + h * 128 + e) = w;
;             }
	v_pk_mul_f32 v[8:9], v[10:11], v[8:9]
	v_pk_mul_f32 v[10:11], v[82:83], v[6:7] op_sel_hi:[1,0]
	v_cvt_pk_bf16_f32 v8, v8, v9
	v_pk_mul_f32 v[10:11], v[12:13], v[10:11]
	v_pk_mul_f32 v[12:13], v[104:105], v[6:7] op_sel_hi:[1,0]
	v_cvt_pk_bf16_f32 v9, v10, v11
	global_store_dwordx2 v[48:49], v[8:9], off
	v_pk_mul_f32 v[2:3], v[2:3], v[6:7] op_sel_hi:[1,0]
	v_pk_mul_f32 v[0:1], v[0:1], v[6:7] op_sel_hi:[1,0]
	v_pk_mul_f32 v[168:169], v[168:169], v[12:13]
	v_pk_mul_f32 v[12:13], v[96:97], v[6:7] op_sel_hi:[1,0]
	v_cvt_pk_bf16_f32 v168, v168, v169
	v_pk_mul_f32 v[170:171], v[170:171], v[12:13]
	v_pk_mul_f32 v[12:13], v[106:107], v[6:7] op_sel_hi:[1,0]
	v_cvt_pk_bf16_f32 v169, v170, v171
	global_store_dwordx2 v[48:49], v[168:169], off offset:16
	v_pk_mul_f32 v[172:173], v[172:173], v[12:13]
	v_pk_mul_f32 v[12:13], v[88:89], v[6:7] op_sel_hi:[1,0]
	v_cvt_pk_bf16_f32 v172, v172, v173
	v_pk_mul_f32 v[174:175], v[174:175], v[12:13]
	v_pk_mul_f32 v[12:13], v[60:61], v[6:7] op_sel_hi:[1,0]
	v_cvt_pk_bf16_f32 v173, v174, v175
	global_store_dwordx2 v[48:49], v[172:173], off offset:32
	v_pk_mul_f32 v[176:177], v[176:177], v[12:13]
	v_pk_mul_f32 v[12:13], v[62:63], v[6:7] op_sel_hi:[1,0]
	v_cvt_pk_bf16_f32 v176, v176, v177
	v_pk_mul_f32 v[178:179], v[178:179], v[12:13]
	v_pk_mul_f32 v[12:13], v[58:59], v[6:7] op_sel_hi:[1,0]
	v_cvt_pk_bf16_f32 v177, v178, v179
	global_store_dwordx2 v[48:49], v[176:177], off offset:48
	v_pk_mul_f32 v[180:181], v[180:181], v[12:13]
	v_pk_mul_f32 v[12:13], v[56:57], v[6:7] op_sel_hi:[1,0]
	v_cvt_pk_bf16_f32 v180, v180, v181
	v_pk_mul_f32 v[182:183], v[182:183], v[12:13]
	v_pk_mul_f32 v[12:13], v[54:55], v[6:7] op_sel_hi:[1,0]
	v_cvt_pk_bf16_f32 v181, v182, v183
	global_store_dwordx2 v[48:49], v[180:181], off offset:64
	v_pk_mul_f32 v[184:185], v[12:13], v[184:185]
	v_pk_mul_f32 v[12:13], v[50:51], v[6:7] op_sel_hi:[1,0]
	v_cvt_pk_bf16_f32 v184, v184, v185
	v_pk_mul_f32 v[186:187], v[12:13], v[186:187]
	v_pk_mul_f32 v[12:13], v[52:53], v[6:7] op_sel_hi:[1,0]
	v_cvt_pk_bf16_f32 v185, v186, v187
	global_store_dwordx2 v[48:49], v[184:185], off offset:80
	v_pk_mul_f32 v[188:189], v[12:13], v[188:189]
	v_pk_mul_f32 v[12:13], v[42:43], v[6:7] op_sel_hi:[1,0]
	v_cvt_pk_bf16_f32 v188, v188, v189
	v_pk_mul_f32 v[190:191], v[12:13], v[190:191]
	v_pk_mul_f32 v[12:13], v[44:45], v[6:7] op_sel_hi:[1,0]
	v_cvt_pk_bf16_f32 v189, v190, v191
	global_store_dwordx2 v[48:49], v[188:189], off offset:96
	v_pk_mul_f32 v[192:193], v[12:13], v[192:193]
	v_pk_mul_f32 v[12:13], v[40:41], v[6:7] op_sel_hi:[1,0]
	v_cvt_pk_bf16_f32 v192, v192, v193
	v_pk_mul_f32 v[194:195], v[12:13], v[194:195]
	v_pk_mul_f32 v[12:13], v[38:39], v[6:7] op_sel_hi:[1,0]
	v_cvt_pk_bf16_f32 v193, v194, v195
	global_store_dwordx2 v[48:49], v[192:193], off offset:112
	v_pk_mul_f32 v[196:197], v[12:13], v[196:197]
	v_pk_mul_f32 v[12:13], v[36:37], v[6:7] op_sel_hi:[1,0]
	v_cvt_pk_bf16_f32 v196, v196, v197
	v_pk_mul_f32 v[198:199], v[12:13], v[198:199]
	v_pk_mul_f32 v[12:13], v[34:35], v[6:7] op_sel_hi:[1,0]
	v_cvt_pk_bf16_f32 v197, v198, v199
	global_store_dwordx2 v[48:49], v[196:197], off offset:128
	v_pk_mul_f32 v[200:201], v[12:13], v[200:201]
	v_pk_mul_f32 v[12:13], v[32:33], v[6:7] op_sel_hi:[1,0]
	v_cvt_pk_bf16_f32 v200, v200, v201
	v_pk_mul_f32 v[202:203], v[12:13], v[202:203]
	v_pk_mul_f32 v[12:13], v[26:27], v[6:7] op_sel_hi:[1,0]
	v_cvt_pk_bf16_f32 v201, v202, v203
	global_store_dwordx2 v[48:49], v[200:201], off offset:144
	v_pk_mul_f32 v[204:205], v[12:13], v[204:205]
	v_pk_mul_f32 v[12:13], v[22:23], v[6:7] op_sel_hi:[1,0]
	v_cvt_pk_bf16_f32 v204, v204, v205
	v_pk_mul_f32 v[206:207], v[12:13], v[206:207]
	v_pk_mul_f32 v[12:13], v[24:25], v[6:7] op_sel_hi:[1,0]
	v_cvt_pk_bf16_f32 v205, v206, v207
	global_store_dwordx2 v[48:49], v[204:205], off offset:160
	v_pk_mul_f32 v[218:219], v[12:13], v[218:219]
	v_pk_mul_f32 v[12:13], v[20:21], v[6:7] op_sel_hi:[1,0]
	v_cvt_pk_bf16_f32 v218, v218, v219
	v_pk_mul_f32 v[220:221], v[12:13], v[220:221]
	v_pk_mul_f32 v[12:13], v[18:19], v[6:7] op_sel_hi:[1,0]
	v_cvt_pk_bf16_f32 v219, v220, v221
	global_store_dwordx2 v[48:49], v[218:219], off offset:176
	v_pk_mul_f32 v[222:223], v[12:13], v[222:223]
	v_pk_mul_f32 v[12:13], v[16:17], v[6:7] op_sel_hi:[1,0]
	v_cvt_pk_bf16_f32 v222, v222, v223
	v_pk_mul_f32 v[224:225], v[12:13], v[224:225]
	s_nop 0
	v_cvt_pk_bf16_f32 v223, v224, v225
	global_store_dwordx2 v[48:49], v[222:223], off offset:192
	v_pk_mul_f32 v[4:5], v[4:5], v[226:227]
	v_pk_mul_f32 v[2:3], v[2:3], v[228:229]
	v_cvt_pk_bf16_f32 v4, v4, v5
	v_cvt_pk_bf16_f32 v5, v2, v3
	global_store_dwordx2 v[48:49], v[4:5], off offset:208
	v_pk_mul_f32 v[0:1], v[0:1], v[230:231]
	v_pk_mul_f32 v[230:231], v[64:65], v[6:7] op_sel_hi:[1,0]
	v_cvt_pk_bf16_f32 v0, v0, v1
	v_pk_mul_f32 v[230:231], v[230:231], v[232:233]
	v_pk_mul_f32 v[232:233], v[66:67], v[6:7] op_sel_hi:[1,0]
	v_cvt_pk_bf16_f32 v1, v230, v231
	global_store_dwordx2 v[48:49], v[0:1], off offset:224
	v_pk_mul_f32 v[234:235], v[232:233], v[234:235]
	v_pk_mul_f32 v[232:233], v[14:15], v[6:7] op_sel_hi:[1,0]
	v_cvt_pk_bf16_f32 v234, v234, v235
	v_pk_mul_f32 v[236:237], v[232:233], v[236:237]
	s_nop 0
	v_cvt_pk_bf16_f32 v235, v236, v237
	global_store_dwordx2 v[48:49], v[234:235], off offset:240
	v_mov_b32_e32 v0, v234
	v_mov_b32_e32 v1, v235
	v_mov_b32_e32 v2, v236
	v_mov_b32_e32 v3, v237
	v_mov_b32_e32 v4, v232
	v_mov_b32_e32 v5, v233
	v_mov_b32_e32 v8, v226
	v_mov_b32_e32 v9, v227
	v_mov_b32_e32 v10, v228
	v_mov_b32_e32 v11, v229
	s_branch .LBB0_761
